# grid barrier: the XCD's last arriver bumps the XCD generation word before its own acquire invalidate (other workgroups released one fence earlier)
# baseline (speedup 1.0000x reference)
; __device__ __forceinline__ unsigned xb_ld(unsigned* p)              { return __hip_atomic_load(p, __ATOMIC_RELAXED, __HIP_MEMORY_SCOPE_AGENT); }
; __device__ __forceinline__ unsigned xb_add(unsigned* p, unsigned v) { return __hip_atomic_fetch_add(p, v, __ATOMIC_RELAXED, __HIP_MEMORY_SCOPE_AGENT); }
; #define XB_SPIN(cond, bar) do { unsigned _sp = 0; while (cond) { __builtin_amdgcn_s_sleep(1); \
;     if ((++_sp & 255u) == 0u) { if (xb_ld(&(bar)[XB_TMO])) break; if (_sp > XB_SPIN_CAP) { atomicAdd(&(bar)[XB_TMO], 1u); break; } } } } while (0)
; __device__ __forceinline__ void xcd_barrier(const XcdBarrier& b) {
;     ...
;         const unsigned old = xb_add(&bar[XB_XSUB(b.x)], 1u);
;         const unsigned gen = old / nloc;
;         if (old + 1u == (gen + 1u) * nloc) {
;             __builtin_amdgcn_fence(__ATOMIC_RELEASE, "agent");
;             asm volatile("s_waitcnt vmcnt(0)" ::: "memory");
;             const unsigned og = xb_add(&bar[XB_TOP], 1u);
;             const unsigned tg = og / nx;
;             if (og + 1u == (tg + 1u) * nx) xb_add(&bar[XB_TOPGEN], 1u);
;             else XB_SPIN(xb_ld(&bar[XB_TOPGEN]) == tg, bar);
;             __builtin_amdgcn_fence(__ATOMIC_ACQUIRE, "agent");
;             xb_add(&bar[XB_XGEN(b.x)], 1u);
;             asm volatile("s_waitcnt vmcnt(0)" ::: "memory");
;         } else {
;             XB_SPIN(xb_ld(&bar[XB_XGEN(b.x)]) == gen, bar);
;             __builtin_amdgcn_fence(__ATOMIC_ACQUIRE, "agent");
;             asm volatile("s_waitcnt vmcnt(0)" ::: "memory");
;         }
.LBB0_344:
	s_or_b64 exec, exec, s[6:7]
	v_mov_b32_e32 v1, 0x2000
	v_mov_b32_e32 v2, 1
	s_waitcnt vmcnt(0)
	global_atomic_add v1, v2, s[0:1] offset:1024
	buffer_inv sc1
	s_waitcnt vmcnt(0)

; __device__ __forceinline__ unsigned xb_ld(unsigned* p)              { return __hip_atomic_load(p, __ATOMIC_RELAXED, __HIP_MEMORY_SCOPE_AGENT); }
; __device__ __forceinline__ unsigned xb_add(unsigned* p, unsigned v) { return __hip_atomic_fetch_add(p, v, __ATOMIC_RELAXED, __HIP_MEMORY_SCOPE_AGENT); }
; #define XB_SPIN(cond, bar) do { unsigned _sp = 0; while (cond) { __builtin_amdgcn_s_sleep(1); \
;     if ((++_sp & 255u) == 0u) { if (xb_ld(&(bar)[XB_TMO])) break; if (_sp > XB_SPIN_CAP) { atomicAdd(&(bar)[XB_TMO], 1u); break; } } } } while (0)
; __device__ __forceinline__ void xcd_barrier(const XcdBarrier& b) {
;     ...
;             if (og + 1u == (tg + 1u) * nx) xb_add(&bar[XB_TOPGEN], 1u);
;             else XB_SPIN(xb_ld(&bar[XB_TOPGEN]) == tg, bar);
;             __builtin_amdgcn_fence(__ATOMIC_ACQUIRE, "agent");
;             xb_add(&bar[XB_XGEN(b.x)], 1u);
;             asm volatile("s_waitcnt vmcnt(0)" ::: "memory");
.LBB0_655:
	s_or_b64 exec, exec, s[6:7]
	v_mov_b32_e32 v1, 0x2000
	v_mov_b32_e32 v2, 1
	s_waitcnt vmcnt(0)
	global_atomic_add v1, v2, s[4:5] offset:1024
	buffer_inv sc1
	s_waitcnt vmcnt(0)
